# GEMM no-gate epilogue rewritten lean (no gate mul/select, scalar row stepping, no vmcnt(0) drain)
# speedup vs baseline: 1.0208x; 1.0027x over previous
;     __device__ __forceinline__ void operator()(const f32x4 (&acc)[2][2][4][2], const Unit& u, int wr, int wc, int fr, int fq) const {
;         const int row0 = u.pm * BM + wr * 64 + fr; const int col0 = u.pn * BM + wc * 32 + 8 * fq;
;         f32x4 gv[2][2];
;         if (gate) { const float* g = gate + (u.pm >> 6) * 6144 + col0;
; #pragma unroll
;             for (int bj = 0; bj < 2; ++bj) { gv[bj][0] = *(const f32x4*)(g + bj * HALF); gv[bj][1] = *(const f32x4*)(g + bj * HALF + 4); } }
.LBB0_413:
	s_and_b64 vcc, exec, s[12:13]
	s_cbranch_vccz .Lepi_lean
	v_lshl_or_b32 v156, s44, 8, v162
	s_mov_b64 s[14:15], -1
	s_and_b64 vcc, exec, s[12:13]
	v_ashrrev_i32_e32 v157, 31, v156
	s_cbranch_vccz .LBB0_415
	s_lshr_b32 s14, s60, 6
	s_mulk_i32 s14, 0x1800
	s_ashr_i32 s15, s14, 31
	s_lshl_b64 s[14:15], s[14:15], 2
	s_add_u32 s14, s4, s14
	s_addc_u32 s15, s5, s15
	v_lshl_add_u64 v[78:79], v[156:157], 2, s[14:15]
	global_load_dwordx4 v[86:89], v[78:79], off
	global_load_dwordx4 v[82:85], v[78:79], off offset:16
	global_load_dwordx4 v[74:77], v[78:79], off offset:528
	s_nop 0
	global_load_dwordx4 v[78:81], v[78:79], off offset:512
	s_mov_b64 s[14:15], 0

; __device__ __forceinline__ unsigned cvt_pk_bf16(float lo, float hi) { unsigned r; asm volatile("v_cvt_pk_bf16_f32 %0, %1, %2" : "=v"(r) : "v"(lo), "v"(hi)); return r; }
;     __device__ __forceinline__ void operator()(const f32x4 (&acc)[2][2][4][2], const Unit& u, int wr, int wc, int fr, int fq) const {
;     ...
;             for (int m = 0; m < 4; ++m) { bf16_t* rowp = O + (size_t)(row0 + ai * HALF + m * 16) * ldc + col0;
; #pragma unroll
;                 for (int bj = 0; bj < 2; ++bj) { f32x4 v0 = acc[ai][bj][m][0], v1 = acc[ai][bj][m][1];
;                     if (gate) { v0 = v0 * gv[bj][0]; v1 = v1 * gv[bj][1]; }
;                     if (act == 1) {
; #pragma unroll
;                         for (int e = 0; e < 4; ++e) { float a = fmaxf(v0[e], 0.f), b = fmaxf(v1[e], 0.f); v0[e] = a * a; v1[e] = b * b; } }
;                     u32x4 w; w.x = cvt_pk_bf16(v0[0], v0[1]); w.y = cvt_pk_bf16(v0[2], v0[3]); w.z = cvt_pk_bf16(v1[0], v1[1]); w.w = cvt_pk_bf16(v1[2], v1[3]);
;                     *(u32x4*)(rowp + bj * HALF) = w; } }
.Lepi_join:
	s_cbranch_vccnz .LBB0_406
	s_andn2_b64 vcc, exec, s[22:23]
	s_cbranch_vccnz .LBB0_405
	s_barrier
	s_branch .LBB0_405
.Lepi_lean:
	v_mul_lo_u32 v164, v160, s76
	s_lshl_b32 s14, s60, 8
	s_mul_hi_u32 s15, s14, s76
	s_mul_i32 s14, s14, s76
	s_lshl_b32 s100, s44, 8
	s_add_u32 s14, s14, s100
	s_addc_u32 s15, s15, 0
	s_lshl_b64 s[14:15], s[14:15], 1
	s_add_u32 s100, s6, s14
	s_addc_u32 s101, s7, s15
	s_lshl_b32 s14, s76, 5
	s_mul_i32 s15, s14, 5
	v_add_lshl_u32 v164, v164, v162, 1
	s_andn2_b64 vcc, exec, s[38:39]
	s_cbranch_vccnz .Lepi_lean_noact
	v_max_f32_e32 v142, 0, v142
	v_max_f32_e32 v143, 0, v143
	v_max_f32_e32 v144, 0, v144
	v_max_f32_e32 v145, 0, v145
	v_max_f32_e32 v138, 0, v138
	v_max_f32_e32 v139, 0, v139
	v_max_f32_e32 v140, 0, v140
	v_max_f32_e32 v141, 0, v141
	v_mul_f32_e32 v142, v142, v142
	v_mul_f32_e32 v143, v143, v143
	v_mul_f32_e32 v144, v144, v144
	v_mul_f32_e32 v145, v145, v145
	v_mul_f32_e32 v138, v138, v138
	v_mul_f32_e32 v139, v139, v139
	v_mul_f32_e32 v140, v140, v140
	v_mul_f32_e32 v141, v141, v141
	v_cvt_pk_bf16_f32 v142, v142, v143
	v_cvt_pk_bf16_f32 v143, v144, v145
	v_cvt_pk_bf16_f32 v144, v138, v139
	v_cvt_pk_bf16_f32 v145, v140, v141
	global_store_dwordx4 v164, v[142:145], s[100:101]
	v_max_f32_e32 v134, 0, v134
	v_max_f32_e32 v135, 0, v135
	v_max_f32_e32 v136, 0, v136
	v_max_f32_e32 v137, 0, v137
	v_max_f32_e32 v130, 0, v130
	v_max_f32_e32 v131, 0, v131
	v_max_f32_e32 v132, 0, v132
	v_max_f32_e32 v133, 0, v133
	v_mul_f32_e32 v134, v134, v134
	v_mul_f32_e32 v135, v135, v135
	v_mul_f32_e32 v136, v136, v136
	v_mul_f32_e32 v137, v137, v137
	v_mul_f32_e32 v130, v130, v130
	v_mul_f32_e32 v131, v131, v131
	v_mul_f32_e32 v132, v132, v132
	v_mul_f32_e32 v133, v133, v133
	v_cvt_pk_bf16_f32 v134, v134, v135
	v_cvt_pk_bf16_f32 v135, v136, v137
	v_cvt_pk_bf16_f32 v136, v130, v131
	v_cvt_pk_bf16_f32 v137, v132, v133
	global_store_dwordx4 v164, v[134:137], s[100:101] offset:256
	s_add_u32 s100, s100, s14
	s_addc_u32 s101, s101, 0
	v_max_f32_e32 v126, 0, v126
	v_max_f32_e32 v127, 0, v127
	v_max_f32_e32 v128, 0, v128
	v_max_f32_e32 v129, 0, v129
	v_max_f32_e32 v122, 0, v122
	v_max_f32_e32 v123, 0, v123
	v_max_f32_e32 v124, 0, v124
	v_max_f32_e32 v125, 0, v125
	v_mul_f32_e32 v126, v126, v126
	v_mul_f32_e32 v127, v127, v127
	v_mul_f32_e32 v128, v128, v128
	v_mul_f32_e32 v129, v129, v129
	v_mul_f32_e32 v122, v122, v122
	v_mul_f32_e32 v123, v123, v123
	v_mul_f32_e32 v124, v124, v124
	v_mul_f32_e32 v125, v125, v125
	v_cvt_pk_bf16_f32 v126, v126, v127
	v_cvt_pk_bf16_f32 v127, v128, v129
	v_cvt_pk_bf16_f32 v128, v122, v123
	v_cvt_pk_bf16_f32 v129, v124, v125
	global_store_dwordx4 v164, v[126:129], s[100:101]
	v_max_f32_e32 v118, 0, v118
	v_max_f32_e32 v119, 0, v119
	v_max_f32_e32 v120, 0, v120
	v_max_f32_e32 v121, 0, v121
	v_max_f32_e32 v114, 0, v114
	v_max_f32_e32 v115, 0, v115
	v_max_f32_e32 v116, 0, v116
	v_max_f32_e32 v117, 0, v117
	v_mul_f32_e32 v118, v118, v118
	v_mul_f32_e32 v119, v119, v119
	v_mul_f32_e32 v120, v120, v120
	v_mul_f32_e32 v121, v121, v121
	v_mul_f32_e32 v114, v114, v114
	v_mul_f32_e32 v115, v115, v115
	v_mul_f32_e32 v116, v116, v116
	v_mul_f32_e32 v117, v117, v117
	v_cvt_pk_bf16_f32 v118, v118, v119
	v_cvt_pk_bf16_f32 v119, v120, v121
	v_cvt_pk_bf16_f32 v120, v114, v115
	v_cvt_pk_bf16_f32 v121, v116, v117
	global_store_dwordx4 v164, v[118:121], s[100:101] offset:256
	s_add_u32 s100, s100, s14
	s_addc_u32 s101, s101, 0
	v_max_f32_e32 v110, 0, v110
	v_max_f32_e32 v111, 0, v111
	v_max_f32_e32 v112, 0, v112
	v_max_f32_e32 v113, 0, v113
	v_max_f32_e32 v106, 0, v106
	v_max_f32_e32 v107, 0, v107
	v_max_f32_e32 v108, 0, v108
	v_max_f32_e32 v109, 0, v109
	v_mul_f32_e32 v110, v110, v110
	v_mul_f32_e32 v111, v111, v111
	v_mul_f32_e32 v112, v112, v112
	v_mul_f32_e32 v113, v113, v113
	v_mul_f32_e32 v106, v106, v106
	v_mul_f32_e32 v107, v107, v107
	v_mul_f32_e32 v108, v108, v108
	v_mul_f32_e32 v109, v109, v109
	v_cvt_pk_bf16_f32 v110, v110, v111
	v_cvt_pk_bf16_f32 v111, v112, v113
	v_cvt_pk_bf16_f32 v112, v106, v107
	v_cvt_pk_bf16_f32 v113, v108, v109
	global_store_dwordx4 v164, v[110:113], s[100:101]
	v_max_f32_e32 v102, 0, v102
	v_max_f32_e32 v103, 0, v103
	v_max_f32_e32 v104, 0, v104
	v_max_f32_e32 v105, 0, v105
	v_max_f32_e32 v98, 0, v98
	v_max_f32_e32 v99, 0, v99
	v_max_f32_e32 v100, 0, v100
	v_max_f32_e32 v101, 0, v101
	v_mul_f32_e32 v102, v102, v102
	v_mul_f32_e32 v103, v103, v103
	v_mul_f32_e32 v104, v104, v104
	v_mul_f32_e32 v105, v105, v105
	v_mul_f32_e32 v98, v98, v98
	v_mul_f32_e32 v99, v99, v99
	v_mul_f32_e32 v100, v100, v100
	v_mul_f32_e32 v101, v101, v101
	v_cvt_pk_bf16_f32 v102, v102, v103
	v_cvt_pk_bf16_f32 v103, v104, v105
	v_cvt_pk_bf16_f32 v104, v98, v99
	v_cvt_pk_bf16_f32 v105, v100, v101
	global_store_dwordx4 v164, v[102:105], s[100:101] offset:256
	s_add_u32 s100, s100, s14
	s_addc_u32 s101, s101, 0
	v_max_f32_e32 v94, 0, v94
	v_max_f32_e32 v95, 0, v95
	v_max_f32_e32 v96, 0, v96
	v_max_f32_e32 v97, 0, v97
	v_max_f32_e32 v90, 0, v90
	v_max_f32_e32 v91, 0, v91
	v_max_f32_e32 v92, 0, v92
	v_max_f32_e32 v93, 0, v93
	v_mul_f32_e32 v94, v94, v94
	v_mul_f32_e32 v95, v95, v95
	v_mul_f32_e32 v96, v96, v96
	v_mul_f32_e32 v97, v97, v97
	v_mul_f32_e32 v90, v90, v90
	v_mul_f32_e32 v91, v91, v91
	v_mul_f32_e32 v92, v92, v92
	v_mul_f32_e32 v93, v93, v93
	v_cvt_pk_bf16_f32 v94, v94, v95
	v_cvt_pk_bf16_f32 v95, v96, v97
	v_cvt_pk_bf16_f32 v96, v90, v91
	v_cvt_pk_bf16_f32 v97, v92, v93
	global_store_dwordx4 v164, v[94:97], s[100:101]
	v_max_f32_e32 v70, 0, v70
	v_max_f32_e32 v71, 0, v71
	v_max_f32_e32 v72, 0, v72
	v_max_f32_e32 v73, 0, v73
	v_max_f32_e32 v66, 0, v66
	v_max_f32_e32 v67, 0, v67
; __device__ __forceinline__ unsigned cvt_pk_bf16(float lo, float hi) { unsigned r; asm volatile("v_cvt_pk_bf16_f32 %0, %1, %2" : "=v"(r) : "v"(lo), "v"(hi)); return r; }
;     __device__ __forceinline__ void operator()(const f32x4 (&acc)[2][2][4][2], const Unit& u, int wr, int wc, int fr, int fq) const {
;     ...
;             for (int m = 0; m < 4; ++m) { bf16_t* rowp = O + (size_t)(row0 + ai * HALF + m * 16) * ldc + col0;
; #pragma unroll
;                 for (int bj = 0; bj < 2; ++bj) { f32x4 v0 = acc[ai][bj][m][0], v1 = acc[ai][bj][m][1];
;                     if (gate) { v0 = v0 * gv[bj][0]; v1 = v1 * gv[bj][1]; }
;                     if (act == 1) {
; #pragma unroll
;                         for (int e = 0; e < 4; ++e) { float a = fmaxf(v0[e], 0.f), b = fmaxf(v1[e], 0.f); v0[e] = a * a; v1[e] = b * b; } }
;                     u32x4 w; w.x = cvt_pk_bf16(v0[0], v0[1]); w.y = cvt_pk_bf16(v0[2], v0[3]); w.z = cvt_pk_bf16(v1[0], v1[1]); w.w = cvt_pk_bf16(v1[2], v1[3]);
;                     *(u32x4*)(rowp + bj * HALF) = w; } }
	v_max_f32_e32 v68, 0, v68
	v_max_f32_e32 v69, 0, v69
	v_mul_f32_e32 v70, v70, v70
	v_mul_f32_e32 v71, v71, v71
	v_mul_f32_e32 v72, v72, v72
	v_mul_f32_e32 v73, v73, v73
	v_mul_f32_e32 v66, v66, v66
	v_mul_f32_e32 v67, v67, v67
	v_mul_f32_e32 v68, v68, v68
	v_mul_f32_e32 v69, v69, v69
	v_cvt_pk_bf16_f32 v70, v70, v71
	v_cvt_pk_bf16_f32 v71, v72, v73
	v_cvt_pk_bf16_f32 v72, v66, v67
	v_cvt_pk_bf16_f32 v73, v68, v69
	global_store_dwordx4 v164, v[70:73], s[100:101] offset:256
	s_add_u32 s100, s100, s15
	s_addc_u32 s101, s101, 0
	v_max_f32_e32 v62, 0, v62
	v_max_f32_e32 v63, 0, v63
	v_max_f32_e32 v64, 0, v64
	v_max_f32_e32 v65, 0, v65
	v_max_f32_e32 v58, 0, v58
	v_max_f32_e32 v59, 0, v59
	v_max_f32_e32 v60, 0, v60
	v_max_f32_e32 v61, 0, v61
	v_mul_f32_e32 v62, v62, v62
	v_mul_f32_e32 v63, v63, v63
	v_mul_f32_e32 v64, v64, v64
	v_mul_f32_e32 v65, v65, v65
	v_mul_f32_e32 v58, v58, v58
	v_mul_f32_e32 v59, v59, v59
	v_mul_f32_e32 v60, v60, v60
	v_mul_f32_e32 v61, v61, v61
	v_cvt_pk_bf16_f32 v62, v62, v63
	v_cvt_pk_bf16_f32 v63, v64, v65
	v_cvt_pk_bf16_f32 v64, v58, v59
	v_cvt_pk_bf16_f32 v65, v60, v61
	global_store_dwordx4 v164, v[62:65], s[100:101]
	v_max_f32_e32 v54, 0, v54
	v_max_f32_e32 v55, 0, v55
	v_max_f32_e32 v56, 0, v56
	v_max_f32_e32 v57, 0, v57
	v_max_f32_e32 v50, 0, v50
	v_max_f32_e32 v51, 0, v51
	v_max_f32_e32 v52, 0, v52
	v_max_f32_e32 v53, 0, v53
	v_mul_f32_e32 v54, v54, v54
	v_mul_f32_e32 v55, v55, v55
	v_mul_f32_e32 v56, v56, v56
	v_mul_f32_e32 v57, v57, v57
	v_mul_f32_e32 v50, v50, v50
	v_mul_f32_e32 v51, v51, v51
	v_mul_f32_e32 v52, v52, v52
	v_mul_f32_e32 v53, v53, v53
	v_cvt_pk_bf16_f32 v54, v54, v55
	v_cvt_pk_bf16_f32 v55, v56, v57
	v_cvt_pk_bf16_f32 v56, v50, v51
	v_cvt_pk_bf16_f32 v57, v52, v53
	global_store_dwordx4 v164, v[54:57], s[100:101] offset:256
	s_add_u32 s100, s100, s14
	s_addc_u32 s101, s101, 0
	v_max_f32_e32 v46, 0, v46
	v_max_f32_e32 v47, 0, v47
	v_max_f32_e32 v48, 0, v48
	v_max_f32_e32 v49, 0, v49
	v_max_f32_e32 v42, 0, v42
	v_max_f32_e32 v43, 0, v43
	v_max_f32_e32 v44, 0, v44
	v_max_f32_e32 v45, 0, v45
	v_mul_f32_e32 v46, v46, v46
	v_mul_f32_e32 v47, v47, v47
	v_mul_f32_e32 v48, v48, v48
	v_mul_f32_e32 v49, v49, v49
	v_mul_f32_e32 v42, v42, v42
	v_mul_f32_e32 v43, v43, v43
	v_mul_f32_e32 v44, v44, v44
	v_mul_f32_e32 v45, v45, v45
	v_cvt_pk_bf16_f32 v46, v46, v47
	v_cvt_pk_bf16_f32 v47, v48, v49
	v_cvt_pk_bf16_f32 v48, v42, v43
	v_cvt_pk_bf16_f32 v49, v44, v45
	global_store_dwordx4 v164, v[46:49], s[100:101]
	v_max_f32_e32 v38, 0, v38
	v_max_f32_e32 v39, 0, v39
	v_max_f32_e32 v40, 0, v40
	v_max_f32_e32 v41, 0, v41
	v_max_f32_e32 v34, 0, v34
	v_max_f32_e32 v35, 0, v35
	v_max_f32_e32 v36, 0, v36
	v_max_f32_e32 v37, 0, v37
	v_mul_f32_e32 v38, v38, v38
	v_mul_f32_e32 v39, v39, v39
	v_mul_f32_e32 v40, v40, v40
	v_mul_f32_e32 v41, v41, v41
	v_mul_f32_e32 v34, v34, v34
	v_mul_f32_e32 v35, v35, v35
	v_mul_f32_e32 v36, v36, v36
	v_mul_f32_e32 v37, v37, v37
	v_cvt_pk_bf16_f32 v38, v38, v39
	v_cvt_pk_bf16_f32 v39, v40, v41
	v_cvt_pk_bf16_f32 v40, v34, v35
	v_cvt_pk_bf16_f32 v41, v36, v37
	global_store_dwordx4 v164, v[38:41], s[100:101] offset:256
	s_add_u32 s100, s100, s14
	s_addc_u32 s101, s101, 0
	v_max_f32_e32 v30, 0, v30
	v_max_f32_e32 v31, 0, v31
	v_max_f32_e32 v32, 0, v32
	v_max_f32_e32 v33, 0, v33
	v_max_f32_e32 v26, 0, v26
	v_max_f32_e32 v27, 0, v27
	v_max_f32_e32 v28, 0, v28
	v_max_f32_e32 v29, 0, v29
	v_mul_f32_e32 v30, v30, v30
	v_mul_f32_e32 v31, v31, v31
	v_mul_f32_e32 v32, v32, v32
	v_mul_f32_e32 v33, v33, v33
	v_mul_f32_e32 v26, v26, v26
	v_mul_f32_e32 v27, v27, v27
	v_mul_f32_e32 v28, v28, v28
	v_mul_f32_e32 v29, v29, v29
	v_cvt_pk_bf16_f32 v30, v30, v31
	v_cvt_pk_bf16_f32 v31, v32, v33
	v_cvt_pk_bf16_f32 v32, v26, v27
	v_cvt_pk_bf16_f32 v33, v28, v29
	global_store_dwordx4 v164, v[30:33], s[100:101]
	v_max_f32_e32 v22, 0, v22
	v_max_f32_e32 v23, 0, v23
	v_max_f32_e32 v24, 0, v24
	v_max_f32_e32 v25, 0, v25
	v_max_f32_e32 v18, 0, v18
	v_max_f32_e32 v19, 0, v19
	v_max_f32_e32 v20, 0, v20
	v_max_f32_e32 v21, 0, v21
	v_mul_f32_e32 v22, v22, v22
	v_mul_f32_e32 v23, v23, v23
	v_mul_f32_e32 v24, v24, v24
	v_mul_f32_e32 v25, v25, v25
	v_mul_f32_e32 v18, v18, v18
	v_mul_f32_e32 v19, v19, v19
	v_mul_f32_e32 v20, v20, v20
	v_mul_f32_e32 v21, v21, v21
	v_cvt_pk_bf16_f32 v22, v22, v23
	v_cvt_pk_bf16_f32 v23, v24, v25
	v_cvt_pk_bf16_f32 v24, v18, v19
	v_cvt_pk_bf16_f32 v25, v20, v21
	global_store_dwordx4 v164, v[22:25], s[100:101] offset:256
	s_add_u32 s100, s100, s14
	s_addc_u32 s101, s101, 0
	v_max_f32_e32 v14, 0, v14
	v_max_f32_e32 v15, 0, v15
	v_max_f32_e32 v16, 0, v16
	v_max_f32_e32 v17, 0, v17
	v_max_f32_e32 v10, 0, v10
	v_max_f32_e32 v11, 0, v11
	v_max_f32_e32 v12, 0, v12
	v_max_f32_e32 v13, 0, v13
	v_mul_f32_e32 v14, v14, v14
	v_mul_f32_e32 v15, v15, v15
	v_mul_f32_e32 v16, v16, v16
	v_mul_f32_e32 v17, v17, v17
	v_mul_f32_e32 v10, v10, v10
	v_mul_f32_e32 v11, v11, v11
	v_mul_f32_e32 v12, v12, v12
	v_mul_f32_e32 v13, v13, v13
	v_cvt_pk_bf16_f32 v14, v14, v15
	v_cvt_pk_bf16_f32 v15, v16, v17
	v_cvt_pk_bf16_f32 v16, v10, v11
	v_cvt_pk_bf16_f32 v17, v12, v13
	global_store_dwordx4 v164, v[14:17], s[100:101]
	v_max_f32_e32 v6, 0, v6
	v_max_f32_e32 v7, 0, v7
	v_max_f32_e32 v8, 0, v8
	v_max_f32_e32 v9, 0, v9
	v_max_f32_e32 v2, 0, v2
	v_max_f32_e32 v3, 0, v3
	v_max_f32_e32 v4, 0, v4
	v_max_f32_e32 v5, 0, v5
	v_mul_f32_e32 v6, v6, v6
	v_mul_f32_e32 v7, v7, v7
	v_mul_f32_e32 v8, v8, v8
	v_mul_f32_e32 v9, v9, v9
	v_mul_f32_e32 v2, v2, v2
	v_mul_f32_e32 v3, v3, v3
	v_mul_f32_e32 v4, v4, v4
	v_mul_f32_e32 v5, v5, v5
	v_cvt_pk_bf16_f32 v6, v6, v7
	v_cvt_pk_bf16_f32 v7, v8, v9
	v_cvt_pk_bf16_f32 v8, v2, v3
	v_cvt_pk_bf16_f32 v9, v4, v5
	global_store_dwordx4 v164, v[6:9], s[100:101] offset:256
	s_andn2_b64 vcc, exec, s[42:43]
	s_mov_b64 s[14:15], -1
	s_branch .Lepi_join
; __device__ __forceinline__ unsigned cvt_pk_bf16(float lo, float hi) { unsigned r; asm volatile("v_cvt_pk_bf16_f32 %0, %1, %2" : "=v"(r) : "v"(lo), "v"(hi)); return r; }
;     __device__ __forceinline__ void operator()(const f32x4 (&acc)[2][2][4][2], const Unit& u, int wr, int wc, int fr, int fq) const {
;     ...
;             for (int m = 0; m < 4; ++m) { bf16_t* rowp = O + (size_t)(row0 + ai * HALF + m * 16) * ldc + col0;
; #pragma unroll
;                 for (int bj = 0; bj < 2; ++bj) { f32x4 v0 = acc[ai][bj][m][0], v1 = acc[ai][bj][m][1];
;                     if (gate) { v0 = v0 * gv[bj][0]; v1 = v1 * gv[bj][1]; }
;                     if (act == 1) {
; #pragma unroll
;                         for (int e = 0; e < 4; ++e) { float a = fmaxf(v0[e], 0.f), b = fmaxf(v1[e], 0.f); v0[e] = a * a; v1[e] = b * b; } }
;                     u32x4 w; w.x = cvt_pk_bf16(v0[0], v0[1]); w.y = cvt_pk_bf16(v0[2], v0[3]); w.z = cvt_pk_bf16(v1[0], v1[1]); w.w = cvt_pk_bf16(v1[2], v1[3]);
;                     *(u32x4*)(rowp + bj * HALF) = w; } }
.Lepi_lean_noact:
	v_cvt_pk_bf16_f32 v142, v142, v143
	v_cvt_pk_bf16_f32 v143, v144, v145
	v_cvt_pk_bf16_f32 v144, v138, v139
	v_cvt_pk_bf16_f32 v145, v140, v141
	global_store_dwordx4 v164, v[142:145], s[100:101]
	v_cvt_pk_bf16_f32 v134, v134, v135
	v_cvt_pk_bf16_f32 v135, v136, v137
	v_cvt_pk_bf16_f32 v136, v130, v131
	v_cvt_pk_bf16_f32 v137, v132, v133
	global_store_dwordx4 v164, v[134:137], s[100:101] offset:256
	s_add_u32 s100, s100, s14
	s_addc_u32 s101, s101, 0
	v_cvt_pk_bf16_f32 v126, v126, v127
	v_cvt_pk_bf16_f32 v127, v128, v129
	v_cvt_pk_bf16_f32 v128, v122, v123
	v_cvt_pk_bf16_f32 v129, v124, v125
	global_store_dwordx4 v164, v[126:129], s[100:101]
	v_cvt_pk_bf16_f32 v118, v118, v119
	v_cvt_pk_bf16_f32 v119, v120, v121
	v_cvt_pk_bf16_f32 v120, v114, v115
	v_cvt_pk_bf16_f32 v121, v116, v117
	global_store_dwordx4 v164, v[118:121], s[100:101] offset:256
	s_add_u32 s100, s100, s14
	s_addc_u32 s101, s101, 0
	v_cvt_pk_bf16_f32 v110, v110, v111
	v_cvt_pk_bf16_f32 v111, v112, v113
	v_cvt_pk_bf16_f32 v112, v106, v107
	v_cvt_pk_bf16_f32 v113, v108, v109
	global_store_dwordx4 v164, v[110:113], s[100:101]
	v_cvt_pk_bf16_f32 v102, v102, v103
	v_cvt_pk_bf16_f32 v103, v104, v105
	v_cvt_pk_bf16_f32 v104, v98, v99
	v_cvt_pk_bf16_f32 v105, v100, v101
	global_store_dwordx4 v164, v[102:105], s[100:101] offset:256
	s_add_u32 s100, s100, s14
	s_addc_u32 s101, s101, 0
	v_cvt_pk_bf16_f32 v94, v94, v95
	v_cvt_pk_bf16_f32 v95, v96, v97
	v_cvt_pk_bf16_f32 v96, v90, v91
	v_cvt_pk_bf16_f32 v97, v92, v93
	global_store_dwordx4 v164, v[94:97], s[100:101]
	v_cvt_pk_bf16_f32 v70, v70, v71
	v_cvt_pk_bf16_f32 v71, v72, v73
	v_cvt_pk_bf16_f32 v72, v66, v67
	v_cvt_pk_bf16_f32 v73, v68, v69
	global_store_dwordx4 v164, v[70:73], s[100:101] offset:256
	s_add_u32 s100, s100, s15
	s_addc_u32 s101, s101, 0
	v_cvt_pk_bf16_f32 v62, v62, v63
	v_cvt_pk_bf16_f32 v63, v64, v65
	v_cvt_pk_bf16_f32 v64, v58, v59
	v_cvt_pk_bf16_f32 v65, v60, v61
	global_store_dwordx4 v164, v[62:65], s[100:101]
	v_cvt_pk_bf16_f32 v54, v54, v55
	v_cvt_pk_bf16_f32 v55, v56, v57
	v_cvt_pk_bf16_f32 v56, v50, v51
	v_cvt_pk_bf16_f32 v57, v52, v53
	global_store_dwordx4 v164, v[54:57], s[100:101] offset:256
	s_add_u32 s100, s100, s14
	s_addc_u32 s101, s101, 0
	v_cvt_pk_bf16_f32 v46, v46, v47
	v_cvt_pk_bf16_f32 v47, v48, v49
	v_cvt_pk_bf16_f32 v48, v42, v43
	v_cvt_pk_bf16_f32 v49, v44, v45
	global_store_dwordx4 v164, v[46:49], s[100:101]
	v_cvt_pk_bf16_f32 v38, v38, v39
	v_cvt_pk_bf16_f32 v39, v40, v41
	v_cvt_pk_bf16_f32 v40, v34, v35
	v_cvt_pk_bf16_f32 v41, v36, v37
	global_store_dwordx4 v164, v[38:41], s[100:101] offset:256
	s_add_u32 s100, s100, s14
	s_addc_u32 s101, s101, 0
	v_cvt_pk_bf16_f32 v30, v30, v31
	v_cvt_pk_bf16_f32 v31, v32, v33
	v_cvt_pk_bf16_f32 v32, v26, v27
	v_cvt_pk_bf16_f32 v33, v28, v29
	global_store_dwordx4 v164, v[30:33], s[100:101]
	v_cvt_pk_bf16_f32 v22, v22, v23
	v_cvt_pk_bf16_f32 v23, v24, v25
	v_cvt_pk_bf16_f32 v24, v18, v19
	v_cvt_pk_bf16_f32 v25, v20, v21
	global_store_dwordx4 v164, v[22:25], s[100:101] offset:256
	s_add_u32 s100, s100, s14
	s_addc_u32 s101, s101, 0
	v_cvt_pk_bf16_f32 v14, v14, v15
	v_cvt_pk_bf16_f32 v15, v16, v17
	v_cvt_pk_bf16_f32 v16, v10, v11
	v_cvt_pk_bf16_f32 v17, v12, v13
	global_store_dwordx4 v164, v[14:17], s[100:101]
	v_cvt_pk_bf16_f32 v6, v6, v7
	v_cvt_pk_bf16_f32 v7, v8, v9
	v_cvt_pk_bf16_f32 v8, v2, v3
	v_cvt_pk_bf16_f32 v9, v4, v5
	global_store_dwordx4 v164, v[6:9], s[100:101] offset:256
	s_andn2_b64 vcc, exec, s[42:43]
	s_mov_b64 s[14:15], -1
	s_branch .Lepi_join
